# v3 plus: sc1 on the gate|up K-loop stage loads
# baseline (speedup 1.0000x reference)
.LBB0_345:
	s_or_b64 exec, exec, s[4:5]
	s_lshr_b32 s0, s22, 3
	s_lshl_b32 s0, s0, 3
	s_sub_i32 s0, s21, s0
	s_lshl_b32 s1, s20, 3
	s_sext_i32_i16 s0, s0
	s_add_i32 s61, s1, s0
	s_lshl_b32 s63, s61, 19
	s_add_u32 s12, s16, 0xa800000
	s_addc_u32 s1, s17, 0
	v_lshl_add_u32 v147, v3, 10, v4
	s_and_b32 s13, s1, 0xffff
	s_mov_b32 s15, 0x20000
	s_mov_b32 s14, -1
	s_barrier
	s_mov_b32 m0, s33
	s_nop 0
	buffer_load_dwordx4 v147, s[12:15], s63 offen sc1 lds
	v_lshl_add_u32 v148, v5, 10, v6
	s_add_i32 s2, s33, 0x2000
	s_mov_b32 m0, s2
	s_nop 0
	buffer_load_dwordx4 v148, s[12:15], s63 offen sc1 lds
	s_add_i32 s3, s33, 0x4000
	s_or_b32 s1, s63, 0x20000
	s_mov_b32 m0, s3
	s_nop 0
	buffer_load_dwordx4 v147, s[12:15], s1 offen sc1 lds
	s_ashr_i32 s0, s24, 8
	s_add_i32 s38, s33, 0x6000
	s_mov_b32 m0, s38
	s_nop 0
	buffer_load_dwordx4 v148, s[12:15], s1 offen sc1 lds
	s_cmp_eq_u32 s0, 1
	s_mov_b32 s58, 0
	s_cselect_b64 s[6:7], -1, 0
	s_cmp_lg_u32 s0, 1
	s_cbranch_scc1 .LBB0_347
	s_barrier
.LBB0_347:
	v_lshrrev_b32_e32 v4, 1, v2
	v_and_b32_e32 v151, 24, v4
	s_add_u32 s20, s16, 0x5000000
	v_and_b32_e32 v3, 63, v2
	v_and_b32_e32 v149, 15, v2
	v_lshlrev_b32_e32 v4, 1, v151
	v_lshlrev_b32_e32 v2, 2, v2
	s_addc_u32 s21, s17, 0
	s_lshl_b32 s39, s0, 6
	v_lshl_or_b32 v4, v149, 6, v4
	s_lshl_b32 s0, s0, 13
	v_and_b32_e32 v2, 32, v2
	v_bitop3_b32 v5, v4, s0, v2 bitop3:0xde
	s_lshl_b32 s0, s25, 5
	s_and_b32 s40, s0, 0x60
	s_lshl_b32 s0, s40, 7
	v_bitop3_b32 v4, v4, s0, v2 bitop3:0xde
	s_waitcnt vmcnt(2)
	s_barrier
	s_add_i32 s41, s33, 0x18000
	s_or_b32 s0, s64, 0x80
	s_mov_b32 m0, s41
	s_nop 0
	buffer_load_dwordx4 v145, s[8:11], s0 offen sc1 lds
	s_add_i32 s42, s33, 0x1a000
	s_mov_b32 m0, s42
	s_nop 0
	buffer_load_dwordx4 v146, s[8:11], s0 offen sc1 lds
	s_add_i32 s43, s33, 0x8000
	s_or_b32 s0, s63, 0x80
	s_mov_b32 m0, s43
	s_nop 0
	buffer_load_dwordx4 v147, s[12:15], s0 offen sc1 lds
	s_add_i32 s44, s33, 0xa000
	s_mov_b32 m0, s44
	s_nop 0
	buffer_load_dwordx4 v148, s[12:15], s0 offen sc1 lds
	s_add_i32 s45, s33, 0x1c000
	s_or_b32 s0, s64, 0x20080
	s_add_i32 s46, s33, 0x1e000
	s_cmp_lt_i32 s25, 4
	s_cselect_b64 s[22:23], -1, 0
	s_and_b32 s4, s24, 0xffffffc0
	s_lshl_b32 s47, s25, 8
	s_add_i32 s48, s33, 0xc000
	s_add_i32 s5, s4, 0xffffff00
	s_ashr_i32 s26, s4, 31
	s_cmpk_lt_u32 s24, 0x100
	s_mov_b32 m0, s45
	s_nop 0
	buffer_load_dwordx4 v145, s[8:11], s0 offen sc1 lds
	s_cselect_b64 s[24:25], -1, 0
	s_add_i32 s49, s33, 0xe000
	s_ashr_i32 s50, s30, 31
	s_mov_b32 m0, s46
	s_nop 0
	buffer_load_dwordx4 v146, s[8:11], s0 offen sc1 lds
	s_mov_b32 s51, 0xfc00000
	s_and_b64 s[0:1], s[22:23], exec
	s_cselect_b32 s0, s51, 0xfc20000
	s_add_u32 s51, s16, s0
	s_addc_u32 s52, s17, 0
	s_and_b64 s[0:1], s[22:23], exec
	s_cselect_b32 s1, s26, 0
	s_cselect_b32 s0, s4, s5
	s_lshl_b64 s[0:1], s[0:1], 2
	s_add_u32 s0, s51, s0
	s_waitcnt vmcnt(6)
	s_addc_u32 s1, s52, s1
	v_lshlrev_b32_e32 v2, 2, v3
	v_mov_b32_e32 v3, 0
	v_lshl_add_u64 v[130:131], s[0:1], 0, v[2:3]
	v_add_u32_e32 v2, 0, v4
	v_or_b32_e32 v150, s39, v149
	v_or_b32_e32 v152, s40, v151
	v_mov_b64_e32 v[132:133], 0x580
	v_mov_b64_e32 v[134:135], 0x57f
	s_movk_i32 s51, 0xb1
	v_add_u32_e32 v153, 0x10000, v2
	v_add_u32_e32 v154, 0x14000, v2
	v_add_u32_e32 v155, 0, v5
	v_add_u32_e32 v156, 0x18000, v2
	v_add_u32_e32 v157, 0x1c000, v2
	s_movk_i32 s52, 0x1600
	s_mov_b32 s26, 0xbfb8aa3b
	s_barrier
	s_branch .LBB0_350

.LBB0_353:
	ds_read_b128 v[136:139], v153
	ds_read_b128 v[140:143], v153 offset:1024
	ds_read_b128 v[158:161], v153 offset:2048
	ds_read_b128 v[162:165], v153 offset:3072
	ds_read_b128 v[166:169], v154
	ds_read_b128 v[170:173], v154 offset:1024
	ds_read_b128 v[174:177], v154 offset:2048
	ds_read_b128 v[178:181], v154 offset:3072
	s_add_i32 s66, s63, 0xfffe0080
	s_cmp_eq_u32 s65, 4
	s_cselect_b32 s68, s1, s66
	s_cselect_b32 s67, s62, s64
	s_or_b32 s66, s68, 0x80
	ds_read_b128 v[182:185], v155
	ds_read_b128 v[186:189], v155 offset:1024
	ds_read_b128 v[190:193], v155 offset:2048
	ds_read_b128 v[194:197], v155 offset:3072
	ds_read_b128 v[198:201], v155 offset:4096
	ds_read_b128 v[202:205], v155 offset:5120
	ds_read_b128 v[206:209], v155 offset:6144
	ds_read_b128 v[210:213], v155 offset:7168
	s_mov_b32 m0, s48
	s_nop 0
	buffer_load_dwordx4 v147, s[12:15], s63 offen sc1 lds
	s_nop 0
	s_mov_b32 m0, s49
	s_nop 0
	buffer_load_dwordx4 v148, s[12:15], s63 offen sc1 lds
	s_waitcnt vmcnt(8)
	s_waitcnt lgkmcnt(0)
	s_barrier
	s_setprio 1
	s_waitcnt lgkmcnt(0)
	v_mfma_i32_16x16x64_i8 v[126:129], v[136:139], v[182:185], v[126:129]
	v_mfma_i32_16x16x64_i8 v[122:125], v[158:161], v[182:185], v[122:125]
	v_mfma_i32_16x16x64_i8 v[118:121], v[136:139], v[190:193], v[118:121]
	v_mfma_i32_16x16x64_i8 v[114:117], v[158:161], v[190:193], v[114:117]
	v_mfma_i32_16x16x64_i8 v[110:113], v[136:139], v[198:201], v[110:113]
	v_mfma_i32_16x16x64_i8 v[106:109], v[158:161], v[198:201], v[106:109]
	v_mfma_i32_16x16x64_i8 v[102:105], v[136:139], v[206:209], v[102:105]
	v_mfma_i32_16x16x64_i8 v[98:101], v[158:161], v[206:209], v[98:101]
	v_mfma_i32_16x16x64_i8 v[126:129], v[140:143], v[186:189], v[126:129]
	v_mfma_i32_16x16x64_i8 v[122:125], v[162:165], v[186:189], v[122:125]
	v_mfma_i32_16x16x64_i8 v[118:121], v[140:143], v[194:197], v[118:121]
	v_mfma_i32_16x16x64_i8 v[114:117], v[162:165], v[194:197], v[114:117]
	v_mfma_i32_16x16x64_i8 v[110:113], v[140:143], v[202:205], v[110:113]
	v_mfma_i32_16x16x64_i8 v[106:109], v[162:165], v[202:205], v[106:109]
	v_mfma_i32_16x16x64_i8 v[102:105], v[140:143], v[210:213], v[102:105]
	v_mfma_i32_16x16x64_i8 v[98:101], v[162:165], v[210:213], v[98:101]
	s_setprio 0
	s_setprio 1
	v_mfma_i32_16x16x64_i8 v[94:97], v[166:169], v[182:185], v[94:97]
	v_mfma_i32_16x16x64_i8 v[90:93], v[174:177], v[182:185], v[90:93]
	v_mfma_i32_16x16x64_i8 v[86:89], v[166:169], v[190:193], v[86:89]
	v_mfma_i32_16x16x64_i8 v[82:85], v[174:177], v[190:193], v[82:85]
	v_mfma_i32_16x16x64_i8 v[78:81], v[166:169], v[198:201], v[78:81]
	v_mfma_i32_16x16x64_i8 v[74:77], v[174:177], v[198:201], v[74:77]
	v_mfma_i32_16x16x64_i8 v[70:73], v[166:169], v[206:209], v[70:73]
	v_mfma_i32_16x16x64_i8 v[66:69], v[174:177], v[206:209], v[66:69]
	v_mfma_i32_16x16x64_i8 v[94:97], v[170:173], v[186:189], v[94:97]
	v_mfma_i32_16x16x64_i8 v[90:93], v[178:181], v[186:189], v[90:93]
	v_mfma_i32_16x16x64_i8 v[86:89], v[170:173], v[194:197], v[86:89]
	v_mfma_i32_16x16x64_i8 v[82:85], v[178:181], v[194:197], v[82:85]
	v_mfma_i32_16x16x64_i8 v[78:81], v[170:173], v[202:205], v[78:81]
	v_mfma_i32_16x16x64_i8 v[74:77], v[178:181], v[202:205], v[74:77]
	v_mfma_i32_16x16x64_i8 v[70:73], v[170:173], v[210:213], v[70:73]
	v_mfma_i32_16x16x64_i8 v[66:69], v[178:181], v[210:213], v[66:69]
	s_setprio 0
	s_barrier
	ds_read_b128 v[182:185], v155 offset:16384
	ds_read_b128 v[186:189], v155 offset:17408
	ds_read_b128 v[190:193], v155 offset:18432
	ds_read_b128 v[194:197], v155 offset:19456
	ds_read_b128 v[198:201], v155 offset:20480
	ds_read_b128 v[202:205], v155 offset:21504
	ds_read_b128 v[206:209], v155 offset:22528
	ds_read_b128 v[210:213], v155 offset:23552
	s_mov_b32 m0, s34
	s_nop 0
	buffer_load_dwordx4 v145, s[8:11], s67 offen sc1 lds
	s_add_i32 s69, s67, 0x20000
	s_mov_b32 m0, s35
	s_nop 0
	buffer_load_dwordx4 v146, s[8:11], s67 offen sc1 lds
	s_nop 0
	s_mov_b32 m0, s36
	s_nop 0
	buffer_load_dwordx4 v145, s[8:11], s69 offen sc1 lds
	s_nop 0
	s_mov_b32 m0, s37
	s_nop 0
	buffer_load_dwordx4 v146, s[8:11], s69 offen sc1 lds
	s_nop 0
	s_mov_b32 m0, s33
	s_nop 0
	buffer_load_dwordx4 v147, s[12:15], s68 offen sc1 lds
	s_nop 0
	s_mov_b32 m0, s2
	s_nop 0
	buffer_load_dwordx4 v148, s[12:15], s68 offen sc1 lds
	s_waitcnt vmcnt(8)
	s_waitcnt lgkmcnt(0)
	s_barrier
	s_setprio 1
	s_waitcnt lgkmcnt(0)
	v_mfma_i32_16x16x64_i8 v[62:65], v[136:139], v[182:185], v[62:65]
	v_mfma_i32_16x16x64_i8 v[58:61], v[158:161], v[182:185], v[58:61]
	v_mfma_i32_16x16x64_i8 v[54:57], v[136:139], v[190:193], v[54:57]
	v_mfma_i32_16x16x64_i8 v[50:53], v[158:161], v[190:193], v[50:53]
	v_mfma_i32_16x16x64_i8 v[46:49], v[136:139], v[198:201], v[46:49]
	v_mfma_i32_16x16x64_i8 v[42:45], v[158:161], v[198:201], v[42:45]
	v_mfma_i32_16x16x64_i8 v[38:41], v[136:139], v[206:209], v[38:41]
	v_mfma_i32_16x16x64_i8 v[34:37], v[158:161], v[206:209], v[34:37]
	v_mfma_i32_16x16x64_i8 v[62:65], v[140:143], v[186:189], v[62:65]
	v_mfma_i32_16x16x64_i8 v[58:61], v[162:165], v[186:189], v[58:61]
	v_mfma_i32_16x16x64_i8 v[54:57], v[140:143], v[194:197], v[54:57]
	v_mfma_i32_16x16x64_i8 v[50:53], v[162:165], v[194:197], v[50:53]
	v_mfma_i32_16x16x64_i8 v[46:49], v[140:143], v[202:205], v[46:49]
	v_mfma_i32_16x16x64_i8 v[42:45], v[162:165], v[202:205], v[42:45]
	v_mfma_i32_16x16x64_i8 v[38:41], v[140:143], v[210:213], v[38:41]
	v_mfma_i32_16x16x64_i8 v[34:37], v[162:165], v[210:213], v[34:37]
	s_setprio 0
	s_setprio 1
	v_mfma_i32_16x16x64_i8 v[30:33], v[166:169], v[182:185], v[30:33]
	v_mfma_i32_16x16x64_i8 v[26:29], v[174:177], v[182:185], v[26:29]
	v_mfma_i32_16x16x64_i8 v[22:25], v[166:169], v[190:193], v[22:25]
	v_mfma_i32_16x16x64_i8 v[18:21], v[174:177], v[190:193], v[18:21]
	v_mfma_i32_16x16x64_i8 v[14:17], v[166:169], v[198:201], v[14:17]
	v_mfma_i32_16x16x64_i8 v[10:13], v[174:177], v[198:201], v[10:13]
	v_mfma_i32_16x16x64_i8 v[6:9], v[166:169], v[206:209], v[6:9]
	v_mfma_i32_16x16x64_i8 v[2:5], v[174:177], v[206:209], v[2:5]
	v_mfma_i32_16x16x64_i8 v[30:33], v[170:173], v[186:189], v[30:33]
	v_mfma_i32_16x16x64_i8 v[26:29], v[178:181], v[186:189], v[26:29]
	v_mfma_i32_16x16x64_i8 v[22:25], v[170:173], v[194:197], v[22:25]
	v_mfma_i32_16x16x64_i8 v[18:21], v[178:181], v[194:197], v[18:21]
	v_mfma_i32_16x16x64_i8 v[14:17], v[170:173], v[202:205], v[14:17]
	v_mfma_i32_16x16x64_i8 v[10:13], v[178:181], v[202:205], v[10:13]
	v_mfma_i32_16x16x64_i8 v[6:9], v[170:173], v[210:213], v[6:9]
	v_mfma_i32_16x16x64_i8 v[2:5], v[178:181], v[210:213], v[2:5]
	s_setprio 0
	s_barrier
	ds_read_b128 v[136:139], v156
	ds_read_b128 v[140:143], v156 offset:1024
	ds_read_b128 v[158:161], v156 offset:2048
	ds_read_b128 v[162:165], v156 offset:3072
	ds_read_b128 v[166:169], v157
	ds_read_b128 v[170:173], v157 offset:1024
	ds_read_b128 v[174:177], v157 offset:2048
	ds_read_b128 v[178:181], v157 offset:3072
	ds_read_b128 v[182:185], v155 offset:32768
	ds_read_b128 v[186:189], v155 offset:33792
	ds_read_b128 v[190:193], v155 offset:34816
	ds_read_b128 v[194:197], v155 offset:35840
	ds_read_b128 v[198:201], v155 offset:36864
	ds_read_b128 v[202:205], v155 offset:37888
	ds_read_b128 v[206:209], v155 offset:38912
	ds_read_b128 v[210:213], v155 offset:39936
	s_add_i32 s68, s68, 0x20000
	s_mov_b32 m0, s3
	s_nop 0
	buffer_load_dwordx4 v147, s[12:15], s68 offen sc1 lds
	s_nop 0
	s_mov_b32 m0, s38
	s_nop 0
	buffer_load_dwordx4 v148, s[12:15], s68 offen sc1 lds
	s_waitcnt vmcnt(8)
	s_waitcnt lgkmcnt(0)
	s_barrier
	s_setprio 1
	s_waitcnt lgkmcnt(0)
	v_mfma_i32_16x16x64_i8 v[126:129], v[136:139], v[182:185], v[126:129]
	v_mfma_i32_16x16x64_i8 v[122:125], v[158:161], v[182:185], v[122:125]
	v_mfma_i32_16x16x64_i8 v[118:121], v[136:139], v[190:193], v[118:121]
	v_mfma_i32_16x16x64_i8 v[114:117], v[158:161], v[190:193], v[114:117]
	v_mfma_i32_16x16x64_i8 v[110:113], v[136:139], v[198:201], v[110:113]
	v_mfma_i32_16x16x64_i8 v[106:109], v[158:161], v[198:201], v[106:109]
	v_mfma_i32_16x16x64_i8 v[102:105], v[136:139], v[206:209], v[102:105]
	v_mfma_i32_16x16x64_i8 v[98:101], v[158:161], v[206:209], v[98:101]
	v_mfma_i32_16x16x64_i8 v[126:129], v[140:143], v[186:189], v[126:129]
	v_mfma_i32_16x16x64_i8 v[122:125], v[162:165], v[186:189], v[122:125]
	v_mfma_i32_16x16x64_i8 v[118:121], v[140:143], v[194:197], v[118:121]
	v_mfma_i32_16x16x64_i8 v[114:117], v[162:165], v[194:197], v[114:117]
	v_mfma_i32_16x16x64_i8 v[110:113], v[140:143], v[202:205], v[110:113]
	v_mfma_i32_16x16x64_i8 v[106:109], v[162:165], v[202:205], v[106:109]
	v_mfma_i32_16x16x64_i8 v[102:105], v[140:143], v[210:213], v[102:105]
	v_mfma_i32_16x16x64_i8 v[98:101], v[162:165], v[210:213], v[98:101]
	s_setprio 0
	s_setprio 1
	v_mfma_i32_16x16x64_i8 v[94:97], v[166:169], v[182:185], v[94:97]
	v_mfma_i32_16x16x64_i8 v[90:93], v[174:177], v[182:185], v[90:93]
	v_mfma_i32_16x16x64_i8 v[86:89], v[166:169], v[190:193], v[86:89]
	v_mfma_i32_16x16x64_i8 v[82:85], v[174:177], v[190:193], v[82:85]
	v_mfma_i32_16x16x64_i8 v[78:81], v[166:169], v[198:201], v[78:81]
	v_mfma_i32_16x16x64_i8 v[74:77], v[174:177], v[198:201], v[74:77]
	v_mfma_i32_16x16x64_i8 v[70:73], v[166:169], v[206:209], v[70:73]
	v_mfma_i32_16x16x64_i8 v[66:69], v[174:177], v[206:209], v[66:69]
	v_mfma_i32_16x16x64_i8 v[94:97], v[170:173], v[186:189], v[94:97]
	v_mfma_i32_16x16x64_i8 v[90:93], v[178:181], v[186:189], v[90:93]
	v_mfma_i32_16x16x64_i8 v[86:89], v[170:173], v[194:197], v[86:89]
	v_mfma_i32_16x16x64_i8 v[82:85], v[178:181], v[194:197], v[82:85]
	v_mfma_i32_16x16x64_i8 v[78:81], v[170:173], v[202:205], v[78:81]
	v_mfma_i32_16x16x64_i8 v[74:77], v[178:181], v[202:205], v[74:77]
	v_mfma_i32_16x16x64_i8 v[70:73], v[170:173], v[210:213], v[70:73]
	v_mfma_i32_16x16x64_i8 v[66:69], v[178:181], v[210:213], v[66:69]
	s_setprio 0
	s_barrier
	ds_read_b128 v[182:185], v155 offset:49152
	ds_read_b128 v[186:189], v155 offset:50176
	ds_read_b128 v[190:193], v155 offset:51200
	ds_read_b128 v[194:197], v155 offset:52224
	ds_read_b128 v[198:201], v155 offset:53248
	ds_read_b128 v[202:205], v155 offset:54272
	ds_read_b128 v[206:209], v155 offset:55296
	ds_read_b128 v[210:213], v155 offset:56320
	s_or_b32 s68, s67, 0x80
	s_mov_b32 m0, s41
	s_nop 0
	buffer_load_dwordx4 v145, s[8:11], s68 offen sc1 lds
	s_add_i32 s67, s67, 0x20080
	s_mov_b32 m0, s42
	s_nop 0
	buffer_load_dwordx4 v146, s[8:11], s68 offen sc1 lds
	s_nop 0
	s_mov_b32 m0, s45
	s_nop 0
	buffer_load_dwordx4 v145, s[8:11], s67 offen sc1 lds
	s_nop 0
	s_mov_b32 m0, s46
	s_nop 0
	buffer_load_dwordx4 v146, s[8:11], s67 offen sc1 lds
	s_nop 0
	s_mov_b32 m0, s43
	s_nop 0
	buffer_load_dwordx4 v147, s[12:15], s66 offen sc1 lds
	s_nop 0
	s_mov_b32 m0, s44
	s_nop 0
	buffer_load_dwordx4 v148, s[12:15], s66 offen sc1 lds
	s_waitcnt vmcnt(8)
	s_waitcnt lgkmcnt(0)
	s_barrier
	s_setprio 1
	s_waitcnt lgkmcnt(0)
	v_mfma_i32_16x16x64_i8 v[62:65], v[136:139], v[182:185], v[62:65]
	v_mfma_i32_16x16x64_i8 v[58:61], v[158:161], v[182:185], v[58:61]
	v_mfma_i32_16x16x64_i8 v[54:57], v[136:139], v[190:193], v[54:57]
	v_mfma_i32_16x16x64_i8 v[50:53], v[158:161], v[190:193], v[50:53]
	v_mfma_i32_16x16x64_i8 v[46:49], v[136:139], v[198:201], v[46:49]
	v_mfma_i32_16x16x64_i8 v[42:45], v[158:161], v[198:201], v[42:45]
	v_mfma_i32_16x16x64_i8 v[38:41], v[136:139], v[206:209], v[38:41]
	v_mfma_i32_16x16x64_i8 v[34:37], v[158:161], v[206:209], v[34:37]
	v_mfma_i32_16x16x64_i8 v[62:65], v[140:143], v[186:189], v[62:65]
	v_mfma_i32_16x16x64_i8 v[58:61], v[162:165], v[186:189], v[58:61]
	v_mfma_i32_16x16x64_i8 v[54:57], v[140:143], v[194:197], v[54:57]
	v_mfma_i32_16x16x64_i8 v[50:53], v[162:165], v[194:197], v[50:53]
	v_mfma_i32_16x16x64_i8 v[46:49], v[140:143], v[202:205], v[46:49]
	v_mfma_i32_16x16x64_i8 v[42:45], v[162:165], v[202:205], v[42:45]
	v_mfma_i32_16x16x64_i8 v[38:41], v[140:143], v[210:213], v[38:41]
	v_mfma_i32_16x16x64_i8 v[34:37], v[162:165], v[210:213], v[34:37]
	s_setprio 0
	s_setprio 1
	v_mfma_i32_16x16x64_i8 v[30:33], v[166:169], v[182:185], v[30:33]
	v_mfma_i32_16x16x64_i8 v[26:29], v[174:177], v[182:185], v[26:29]
	v_mfma_i32_16x16x64_i8 v[22:25], v[166:169], v[190:193], v[22:25]
	v_mfma_i32_16x16x64_i8 v[18:21], v[174:177], v[190:193], v[18:21]
	v_mfma_i32_16x16x64_i8 v[14:17], v[166:169], v[198:201], v[14:17]
	v_mfma_i32_16x16x64_i8 v[10:13], v[174:177], v[198:201], v[10:13]
	v_mfma_i32_16x16x64_i8 v[6:9], v[166:169], v[206:209], v[6:9]
	v_mfma_i32_16x16x64_i8 v[2:5], v[174:177], v[206:209], v[2:5]
	v_mfma_i32_16x16x64_i8 v[30:33], v[170:173], v[186:189], v[30:33]
	v_mfma_i32_16x16x64_i8 v[26:29], v[178:181], v[186:189], v[26:29]
	v_mfma_i32_16x16x64_i8 v[22:25], v[170:173], v[194:197], v[22:25]
	v_mfma_i32_16x16x64_i8 v[18:21], v[178:181], v[194:197], v[18:21]
	v_mfma_i32_16x16x64_i8 v[14:17], v[170:173], v[202:205], v[14:17]
	v_mfma_i32_16x16x64_i8 v[10:13], v[178:181], v[202:205], v[10:13]
	v_mfma_i32_16x16x64_i8 v[6:9], v[170:173], v[210:213], v[6:9]
	v_mfma_i32_16x16x64_i8 v[2:5], v[178:181], v[210:213], v[2:5]
	s_setprio 0
	s_barrier
	s_add_i32 s65, s65, 2
	s_addk_i32 s63, 0x100
	s_addk_i32 s64, 0x100
	s_cmp_gt_u32 s65, 5
	s_cbranch_scc0 .LBB0_353
	s_and_b64 vcc, exec, s[24:25]
	s_cbranch_vccz .LBB0_356
	s_barrier

.LBB0_1064:
	s_or_b64 exec, exec, s[6:7]
	s_lshr_b32 s2, s22, 3
	s_lshl_b32 s2, s2, 3
	s_sub_i32 s2, s19, s2
	s_lshl_b32 s3, s18, 3
	s_sext_i32_i16 s2, s2
	s_add_i32 s53, s3, s2
	s_lshl_b32 s55, s53, 19
	s_add_u32 s12, s0, 0xa800000
	s_addc_u32 s2, s1, 0
	v_lshl_add_u32 v146, v3, 10, v4
	s_and_b32 s13, s2, 0xffff
	s_mov_b32 s15, 0x20000
	s_mov_b32 s14, -1
	s_barrier
	s_mov_b32 m0, s26
	s_nop 0
	buffer_load_dwordx4 v146, s[12:15], s55 offen sc1 lds
	v_lshl_add_u32 v147, v5, 10, v6
	s_add_i32 s2, s26, 0x2000
	s_mov_b32 m0, s2
	s_nop 0
	buffer_load_dwordx4 v147, s[12:15], s55 offen sc1 lds
	s_add_i32 s3, s26, 0x4000
	s_or_b32 s5, s55, 0x20000
	s_mov_b32 m0, s3
	s_nop 0
	buffer_load_dwordx4 v146, s[12:15], s5 offen sc1 lds
	s_ashr_i32 s4, s20, 8
	s_add_i32 s31, s26, 0x6000
	s_mov_b32 m0, s31
	s_nop 0
	buffer_load_dwordx4 v147, s[12:15], s5 offen sc1 lds
	s_cmp_eq_u32 s4, 1
	s_mov_b32 s50, 0
	s_cselect_b64 s[6:7], -1, 0
	s_cmp_lg_u32 s4, 1
	s_cbranch_scc1 .LBB0_1066
	s_barrier
.LBB0_1066:
	v_lshrrev_b32_e32 v4, 1, v2
	v_and_b32_e32 v150, 24, v4
	s_add_u32 s16, s0, 0x5000000
	v_and_b32_e32 v3, 63, v2
	v_and_b32_e32 v148, 15, v2
	v_lshlrev_b32_e32 v4, 1, v150
	v_lshlrev_b32_e32 v2, 2, v2
	s_addc_u32 s17, s1, 0
	s_lshl_b32 s33, s4, 6
	v_lshl_or_b32 v4, v148, 6, v4
	s_lshl_b32 s4, s4, 13
	v_and_b32_e32 v2, 32, v2
	v_bitop3_b32 v5, v4, s4, v2 bitop3:0xde
	s_lshl_b32 s4, s21, 5
	s_and_b32 s34, s4, 0x60
	s_lshl_b32 s4, s34, 7
	v_bitop3_b32 v4, v4, s4, v2 bitop3:0xde
	s_waitcnt vmcnt(2)
	s_barrier
	s_add_i32 s35, s26, 0x18000
	s_or_b32 s4, s58, 0x80
	s_mov_b32 m0, s35
	s_nop 0
	buffer_load_dwordx4 v144, s[8:11], s4 offen sc1 lds
	s_add_i32 s36, s26, 0x1a000
	s_mov_b32 m0, s36
	s_nop 0
	buffer_load_dwordx4 v145, s[8:11], s4 offen sc1 lds
	s_add_i32 s37, s26, 0x8000
	s_or_b32 s4, s55, 0x80
	s_mov_b32 m0, s37
	s_nop 0
	buffer_load_dwordx4 v146, s[12:15], s4 offen sc1 lds
	s_add_i32 s38, s26, 0xa000
	s_mov_b32 m0, s38
	s_nop 0
	buffer_load_dwordx4 v147, s[12:15], s4 offen sc1 lds
	s_add_i32 s39, s26, 0x1c000
	s_or_b32 s4, s58, 0x20080
	s_add_i32 s40, s26, 0x1e000
	s_cmp_lt_i32 s21, 4
	s_cselect_b64 s[18:19], -1, 0
	s_and_b32 s22, s20, 0xffffffc0
	s_lshl_b32 s41, s21, 8
	s_add_i32 s42, s26, 0xc000
	s_add_i32 s45, s22, 0xffffff00
	s_ashr_i32 s46, s22, 31
	s_cmpk_lt_u32 s20, 0x100
	s_mov_b32 m0, s39
	s_nop 0
	buffer_load_dwordx4 v144, s[8:11], s4 offen sc1 lds
	s_cselect_b64 s[20:21], -1, 0
	s_add_i32 s43, s26, 0xe000
	s_ashr_i32 s44, s23, 31
	s_mov_b32 m0, s40
	s_nop 0
	buffer_load_dwordx4 v145, s[8:11], s4 offen sc1 lds
	s_mov_b32 s47, 0xfc00000
	s_and_b64 s[4:5], s[18:19], exec
	s_cselect_b32 s4, s47, 0xfc25800
	s_add_u32 s4, s0, s4
	s_addc_u32 s5, s1, 0
	s_and_b64 s[0:1], s[18:19], exec
	s_cselect_b32 s1, s46, 0
	s_cselect_b32 s0, s22, s45
	s_lshl_b64 s[0:1], s[0:1], 2
	s_add_u32 s0, s4, s0
	s_waitcnt vmcnt(6)
	s_addc_u32 s1, s5, s1
	v_lshlrev_b32_e32 v2, 2, v3
	v_mov_b32_e32 v3, 0
	v_lshl_add_u64 v[130:131], s[0:1], 0, v[2:3]
	v_add_u32_e32 v2, 0, v4
	v_or_b32_e32 v149, s33, v148
	v_or_b32_e32 v151, s34, v150
	v_mov_b64_e32 v[132:133], 0x580
	v_mov_b64_e32 v[134:135], 0x57f
	s_movk_i32 s45, 0xb1
	v_add_u32_e32 v152, 0x10000, v2
	v_add_u32_e32 v153, 0x14000, v2
	v_add_u32_e32 v154, 0, v5
	v_add_u32_e32 v155, 0x18000, v2
	v_add_u32_e32 v156, 0x1c000, v2
	s_movk_i32 s46, 0x1600
	s_mov_b32 s22, 0xbfb8aa3b
	s_barrier
	s_branch .LBB0_1069

.LBB0_1072:
	ds_read_b128 v[136:139], v152
	ds_read_b128 v[140:143], v152 offset:1024
	ds_read_b128 v[158:161], v152 offset:2048
	ds_read_b128 v[162:165], v152 offset:3072
	ds_read_b128 v[166:169], v153
	ds_read_b128 v[170:173], v153 offset:1024
	ds_read_b128 v[174:177], v153 offset:2048
	ds_read_b128 v[178:181], v153 offset:3072
	s_add_i32 s60, s55, 0xfffe0080
	s_cmp_eq_u32 s59, 4
	s_cselect_b32 s62, s1, s60
	s_cselect_b32 s61, s54, s58
	s_or_b32 s60, s62, 0x80
	ds_read_b128 v[182:185], v154
	ds_read_b128 v[186:189], v154 offset:1024
	ds_read_b128 v[190:193], v154 offset:2048
	ds_read_b128 v[194:197], v154 offset:3072
	ds_read_b128 v[198:201], v154 offset:4096
	ds_read_b128 v[202:205], v154 offset:5120
	ds_read_b128 v[206:209], v154 offset:6144
	ds_read_b128 v[210:213], v154 offset:7168
	s_mov_b32 m0, s42
	s_nop 0
	buffer_load_dwordx4 v146, s[12:15], s55 offen sc1 lds
	s_nop 0
	s_mov_b32 m0, s43
	s_nop 0
	buffer_load_dwordx4 v147, s[12:15], s55 offen sc1 lds
	s_waitcnt vmcnt(8)
	s_waitcnt lgkmcnt(0)
	s_barrier
	s_setprio 1
	s_waitcnt lgkmcnt(0)
	v_mfma_i32_16x16x64_i8 v[126:129], v[136:139], v[182:185], v[126:129]
	v_mfma_i32_16x16x64_i8 v[122:125], v[158:161], v[182:185], v[122:125]
	v_mfma_i32_16x16x64_i8 v[118:121], v[136:139], v[190:193], v[118:121]
	v_mfma_i32_16x16x64_i8 v[114:117], v[158:161], v[190:193], v[114:117]
	v_mfma_i32_16x16x64_i8 v[110:113], v[136:139], v[198:201], v[110:113]
	v_mfma_i32_16x16x64_i8 v[106:109], v[158:161], v[198:201], v[106:109]
	v_mfma_i32_16x16x64_i8 v[102:105], v[136:139], v[206:209], v[102:105]
	v_mfma_i32_16x16x64_i8 v[98:101], v[158:161], v[206:209], v[98:101]
	v_mfma_i32_16x16x64_i8 v[126:129], v[140:143], v[186:189], v[126:129]
	v_mfma_i32_16x16x64_i8 v[122:125], v[162:165], v[186:189], v[122:125]
	v_mfma_i32_16x16x64_i8 v[118:121], v[140:143], v[194:197], v[118:121]
	v_mfma_i32_16x16x64_i8 v[114:117], v[162:165], v[194:197], v[114:117]
	v_mfma_i32_16x16x64_i8 v[110:113], v[140:143], v[202:205], v[110:113]
	v_mfma_i32_16x16x64_i8 v[106:109], v[162:165], v[202:205], v[106:109]
	v_mfma_i32_16x16x64_i8 v[102:105], v[140:143], v[210:213], v[102:105]
	v_mfma_i32_16x16x64_i8 v[98:101], v[162:165], v[210:213], v[98:101]
	s_setprio 0
	s_setprio 1
	v_mfma_i32_16x16x64_i8 v[94:97], v[166:169], v[182:185], v[94:97]
	v_mfma_i32_16x16x64_i8 v[90:93], v[174:177], v[182:185], v[90:93]
	v_mfma_i32_16x16x64_i8 v[86:89], v[166:169], v[190:193], v[86:89]
	v_mfma_i32_16x16x64_i8 v[82:85], v[174:177], v[190:193], v[82:85]
	v_mfma_i32_16x16x64_i8 v[78:81], v[166:169], v[198:201], v[78:81]
	v_mfma_i32_16x16x64_i8 v[74:77], v[174:177], v[198:201], v[74:77]
	v_mfma_i32_16x16x64_i8 v[70:73], v[166:169], v[206:209], v[70:73]
	v_mfma_i32_16x16x64_i8 v[66:69], v[174:177], v[206:209], v[66:69]
	v_mfma_i32_16x16x64_i8 v[94:97], v[170:173], v[186:189], v[94:97]
	v_mfma_i32_16x16x64_i8 v[90:93], v[178:181], v[186:189], v[90:93]
	v_mfma_i32_16x16x64_i8 v[86:89], v[170:173], v[194:197], v[86:89]
	v_mfma_i32_16x16x64_i8 v[82:85], v[178:181], v[194:197], v[82:85]
	v_mfma_i32_16x16x64_i8 v[78:81], v[170:173], v[202:205], v[78:81]
	v_mfma_i32_16x16x64_i8 v[74:77], v[178:181], v[202:205], v[74:77]
	v_mfma_i32_16x16x64_i8 v[70:73], v[170:173], v[210:213], v[70:73]
	v_mfma_i32_16x16x64_i8 v[66:69], v[178:181], v[210:213], v[66:69]
	s_setprio 0
	s_barrier
	ds_read_b128 v[182:185], v154 offset:16384
	ds_read_b128 v[186:189], v154 offset:17408
	ds_read_b128 v[190:193], v154 offset:18432
	ds_read_b128 v[194:197], v154 offset:19456
	ds_read_b128 v[198:201], v154 offset:20480
	ds_read_b128 v[202:205], v154 offset:21504
	ds_read_b128 v[206:209], v154 offset:22528
	ds_read_b128 v[210:213], v154 offset:23552
	s_mov_b32 m0, s27
	s_nop 0
	buffer_load_dwordx4 v144, s[8:11], s61 offen sc1 lds
	s_add_i32 s63, s61, 0x20000
	s_mov_b32 m0, s28
	s_nop 0
	buffer_load_dwordx4 v145, s[8:11], s61 offen sc1 lds
	s_nop 0
	s_mov_b32 m0, s29
	s_nop 0
	buffer_load_dwordx4 v144, s[8:11], s63 offen sc1 lds
	s_nop 0
	s_mov_b32 m0, s30
	s_nop 0
	buffer_load_dwordx4 v145, s[8:11], s63 offen sc1 lds
	s_nop 0
	s_mov_b32 m0, s26
	s_nop 0
	buffer_load_dwordx4 v146, s[12:15], s62 offen sc1 lds
	s_nop 0
	s_mov_b32 m0, s2
	s_nop 0
	buffer_load_dwordx4 v147, s[12:15], s62 offen sc1 lds
	s_waitcnt vmcnt(8)
	s_waitcnt lgkmcnt(0)
	s_barrier
	s_setprio 1
	s_waitcnt lgkmcnt(0)
	v_mfma_i32_16x16x64_i8 v[62:65], v[136:139], v[182:185], v[62:65]
	v_mfma_i32_16x16x64_i8 v[58:61], v[158:161], v[182:185], v[58:61]
	v_mfma_i32_16x16x64_i8 v[54:57], v[136:139], v[190:193], v[54:57]
	v_mfma_i32_16x16x64_i8 v[50:53], v[158:161], v[190:193], v[50:53]
	v_mfma_i32_16x16x64_i8 v[46:49], v[136:139], v[198:201], v[46:49]
	v_mfma_i32_16x16x64_i8 v[42:45], v[158:161], v[198:201], v[42:45]
	v_mfma_i32_16x16x64_i8 v[38:41], v[136:139], v[206:209], v[38:41]
	v_mfma_i32_16x16x64_i8 v[34:37], v[158:161], v[206:209], v[34:37]
	v_mfma_i32_16x16x64_i8 v[62:65], v[140:143], v[186:189], v[62:65]
	v_mfma_i32_16x16x64_i8 v[58:61], v[162:165], v[186:189], v[58:61]
	v_mfma_i32_16x16x64_i8 v[54:57], v[140:143], v[194:197], v[54:57]
	v_mfma_i32_16x16x64_i8 v[50:53], v[162:165], v[194:197], v[50:53]
	v_mfma_i32_16x16x64_i8 v[46:49], v[140:143], v[202:205], v[46:49]
	v_mfma_i32_16x16x64_i8 v[42:45], v[162:165], v[202:205], v[42:45]
	v_mfma_i32_16x16x64_i8 v[38:41], v[140:143], v[210:213], v[38:41]
	v_mfma_i32_16x16x64_i8 v[34:37], v[162:165], v[210:213], v[34:37]
	s_setprio 0
	s_setprio 1
	v_mfma_i32_16x16x64_i8 v[30:33], v[166:169], v[182:185], v[30:33]
	v_mfma_i32_16x16x64_i8 v[26:29], v[174:177], v[182:185], v[26:29]
	v_mfma_i32_16x16x64_i8 v[22:25], v[166:169], v[190:193], v[22:25]
	v_mfma_i32_16x16x64_i8 v[18:21], v[174:177], v[190:193], v[18:21]
	v_mfma_i32_16x16x64_i8 v[14:17], v[166:169], v[198:201], v[14:17]
	v_mfma_i32_16x16x64_i8 v[10:13], v[174:177], v[198:201], v[10:13]
	v_mfma_i32_16x16x64_i8 v[6:9], v[166:169], v[206:209], v[6:9]
	v_mfma_i32_16x16x64_i8 v[2:5], v[174:177], v[206:209], v[2:5]
	v_mfma_i32_16x16x64_i8 v[30:33], v[170:173], v[186:189], v[30:33]
	v_mfma_i32_16x16x64_i8 v[26:29], v[178:181], v[186:189], v[26:29]
	v_mfma_i32_16x16x64_i8 v[22:25], v[170:173], v[194:197], v[22:25]
	v_mfma_i32_16x16x64_i8 v[18:21], v[178:181], v[194:197], v[18:21]
	v_mfma_i32_16x16x64_i8 v[14:17], v[170:173], v[202:205], v[14:17]
	v_mfma_i32_16x16x64_i8 v[10:13], v[178:181], v[202:205], v[10:13]
	v_mfma_i32_16x16x64_i8 v[6:9], v[170:173], v[210:213], v[6:9]
	v_mfma_i32_16x16x64_i8 v[2:5], v[178:181], v[210:213], v[2:5]
	s_setprio 0
	s_barrier
	ds_read_b128 v[136:139], v155
	ds_read_b128 v[140:143], v155 offset:1024
	ds_read_b128 v[158:161], v155 offset:2048
	ds_read_b128 v[162:165], v155 offset:3072
	ds_read_b128 v[166:169], v156
	ds_read_b128 v[170:173], v156 offset:1024
	ds_read_b128 v[174:177], v156 offset:2048
	ds_read_b128 v[178:181], v156 offset:3072
	ds_read_b128 v[182:185], v154 offset:32768
	ds_read_b128 v[186:189], v154 offset:33792
	ds_read_b128 v[190:193], v154 offset:34816
	ds_read_b128 v[194:197], v154 offset:35840
	ds_read_b128 v[198:201], v154 offset:36864
	ds_read_b128 v[202:205], v154 offset:37888
	ds_read_b128 v[206:209], v154 offset:38912
	ds_read_b128 v[210:213], v154 offset:39936
	s_add_i32 s62, s62, 0x20000
	s_mov_b32 m0, s3
	s_nop 0
	buffer_load_dwordx4 v146, s[12:15], s62 offen sc1 lds
	s_nop 0
	s_mov_b32 m0, s31
	s_nop 0
	buffer_load_dwordx4 v147, s[12:15], s62 offen sc1 lds
	s_waitcnt vmcnt(8)
	s_waitcnt lgkmcnt(0)
	s_barrier
	s_setprio 1
	s_waitcnt lgkmcnt(0)
	v_mfma_i32_16x16x64_i8 v[126:129], v[136:139], v[182:185], v[126:129]
	v_mfma_i32_16x16x64_i8 v[122:125], v[158:161], v[182:185], v[122:125]
	v_mfma_i32_16x16x64_i8 v[118:121], v[136:139], v[190:193], v[118:121]
	v_mfma_i32_16x16x64_i8 v[114:117], v[158:161], v[190:193], v[114:117]
	v_mfma_i32_16x16x64_i8 v[110:113], v[136:139], v[198:201], v[110:113]
	v_mfma_i32_16x16x64_i8 v[106:109], v[158:161], v[198:201], v[106:109]
	v_mfma_i32_16x16x64_i8 v[102:105], v[136:139], v[206:209], v[102:105]
	v_mfma_i32_16x16x64_i8 v[98:101], v[158:161], v[206:209], v[98:101]
	v_mfma_i32_16x16x64_i8 v[126:129], v[140:143], v[186:189], v[126:129]
	v_mfma_i32_16x16x64_i8 v[122:125], v[162:165], v[186:189], v[122:125]
	v_mfma_i32_16x16x64_i8 v[118:121], v[140:143], v[194:197], v[118:121]
	v_mfma_i32_16x16x64_i8 v[114:117], v[162:165], v[194:197], v[114:117]
	v_mfma_i32_16x16x64_i8 v[110:113], v[140:143], v[202:205], v[110:113]
	v_mfma_i32_16x16x64_i8 v[106:109], v[162:165], v[202:205], v[106:109]
	v_mfma_i32_16x16x64_i8 v[102:105], v[140:143], v[210:213], v[102:105]
	v_mfma_i32_16x16x64_i8 v[98:101], v[162:165], v[210:213], v[98:101]
	s_setprio 0
	s_setprio 1
	v_mfma_i32_16x16x64_i8 v[94:97], v[166:169], v[182:185], v[94:97]
	v_mfma_i32_16x16x64_i8 v[90:93], v[174:177], v[182:185], v[90:93]
	v_mfma_i32_16x16x64_i8 v[86:89], v[166:169], v[190:193], v[86:89]
	v_mfma_i32_16x16x64_i8 v[82:85], v[174:177], v[190:193], v[82:85]
	v_mfma_i32_16x16x64_i8 v[78:81], v[166:169], v[198:201], v[78:81]
	v_mfma_i32_16x16x64_i8 v[74:77], v[174:177], v[198:201], v[74:77]
	v_mfma_i32_16x16x64_i8 v[70:73], v[166:169], v[206:209], v[70:73]
	v_mfma_i32_16x16x64_i8 v[66:69], v[174:177], v[206:209], v[66:69]
	v_mfma_i32_16x16x64_i8 v[94:97], v[170:173], v[186:189], v[94:97]
	v_mfma_i32_16x16x64_i8 v[90:93], v[178:181], v[186:189], v[90:93]
	v_mfma_i32_16x16x64_i8 v[86:89], v[170:173], v[194:197], v[86:89]
	v_mfma_i32_16x16x64_i8 v[82:85], v[178:181], v[194:197], v[82:85]
	v_mfma_i32_16x16x64_i8 v[78:81], v[170:173], v[202:205], v[78:81]
	v_mfma_i32_16x16x64_i8 v[74:77], v[178:181], v[202:205], v[74:77]
	v_mfma_i32_16x16x64_i8 v[70:73], v[170:173], v[210:213], v[70:73]
	v_mfma_i32_16x16x64_i8 v[66:69], v[178:181], v[210:213], v[66:69]
	s_setprio 0
	s_barrier
	ds_read_b128 v[182:185], v154 offset:49152
	ds_read_b128 v[186:189], v154 offset:50176
	ds_read_b128 v[190:193], v154 offset:51200
	ds_read_b128 v[194:197], v154 offset:52224
	ds_read_b128 v[198:201], v154 offset:53248
	ds_read_b128 v[202:205], v154 offset:54272
	ds_read_b128 v[206:209], v154 offset:55296
	ds_read_b128 v[210:213], v154 offset:56320
	s_or_b32 s62, s61, 0x80
	s_mov_b32 m0, s35
	s_nop 0
	buffer_load_dwordx4 v144, s[8:11], s62 offen sc1 lds
	s_add_i32 s61, s61, 0x20080
	s_mov_b32 m0, s36
	s_nop 0
	buffer_load_dwordx4 v145, s[8:11], s62 offen sc1 lds
	s_nop 0
	s_mov_b32 m0, s39
	s_nop 0
	buffer_load_dwordx4 v144, s[8:11], s61 offen sc1 lds
	s_nop 0
	s_mov_b32 m0, s40
	s_nop 0
	buffer_load_dwordx4 v145, s[8:11], s61 offen sc1 lds
	s_nop 0
	s_mov_b32 m0, s37
	s_nop 0
	buffer_load_dwordx4 v146, s[12:15], s60 offen sc1 lds
	s_nop 0
	s_mov_b32 m0, s38
	s_nop 0
	buffer_load_dwordx4 v147, s[12:15], s60 offen sc1 lds
	s_waitcnt vmcnt(8)
	s_waitcnt lgkmcnt(0)
	s_barrier
	s_setprio 1
	s_waitcnt lgkmcnt(0)
	v_mfma_i32_16x16x64_i8 v[62:65], v[136:139], v[182:185], v[62:65]
	v_mfma_i32_16x16x64_i8 v[58:61], v[158:161], v[182:185], v[58:61]
	v_mfma_i32_16x16x64_i8 v[54:57], v[136:139], v[190:193], v[54:57]
	v_mfma_i32_16x16x64_i8 v[50:53], v[158:161], v[190:193], v[50:53]
	v_mfma_i32_16x16x64_i8 v[46:49], v[136:139], v[198:201], v[46:49]
	v_mfma_i32_16x16x64_i8 v[42:45], v[158:161], v[198:201], v[42:45]
	v_mfma_i32_16x16x64_i8 v[38:41], v[136:139], v[206:209], v[38:41]
	v_mfma_i32_16x16x64_i8 v[34:37], v[158:161], v[206:209], v[34:37]
	v_mfma_i32_16x16x64_i8 v[62:65], v[140:143], v[186:189], v[62:65]
	v_mfma_i32_16x16x64_i8 v[58:61], v[162:165], v[186:189], v[58:61]
	v_mfma_i32_16x16x64_i8 v[54:57], v[140:143], v[194:197], v[54:57]
	v_mfma_i32_16x16x64_i8 v[50:53], v[162:165], v[194:197], v[50:53]
	v_mfma_i32_16x16x64_i8 v[46:49], v[140:143], v[202:205], v[46:49]
	v_mfma_i32_16x16x64_i8 v[42:45], v[162:165], v[202:205], v[42:45]
	v_mfma_i32_16x16x64_i8 v[38:41], v[140:143], v[210:213], v[38:41]
	v_mfma_i32_16x16x64_i8 v[34:37], v[162:165], v[210:213], v[34:37]
	s_setprio 0
	s_setprio 1
	v_mfma_i32_16x16x64_i8 v[30:33], v[166:169], v[182:185], v[30:33]
	v_mfma_i32_16x16x64_i8 v[26:29], v[174:177], v[182:185], v[26:29]
	v_mfma_i32_16x16x64_i8 v[22:25], v[166:169], v[190:193], v[22:25]
	v_mfma_i32_16x16x64_i8 v[18:21], v[174:177], v[190:193], v[18:21]
	v_mfma_i32_16x16x64_i8 v[14:17], v[166:169], v[198:201], v[14:17]
	v_mfma_i32_16x16x64_i8 v[10:13], v[174:177], v[198:201], v[10:13]
	v_mfma_i32_16x16x64_i8 v[6:9], v[166:169], v[206:209], v[6:9]
	v_mfma_i32_16x16x64_i8 v[2:5], v[174:177], v[206:209], v[2:5]
	v_mfma_i32_16x16x64_i8 v[30:33], v[170:173], v[186:189], v[30:33]
	v_mfma_i32_16x16x64_i8 v[26:29], v[178:181], v[186:189], v[26:29]
	v_mfma_i32_16x16x64_i8 v[22:25], v[170:173], v[194:197], v[22:25]
	v_mfma_i32_16x16x64_i8 v[18:21], v[178:181], v[194:197], v[18:21]
	v_mfma_i32_16x16x64_i8 v[14:17], v[170:173], v[202:205], v[14:17]
	v_mfma_i32_16x16x64_i8 v[10:13], v[178:181], v[202:205], v[10:13]
	v_mfma_i32_16x16x64_i8 v[6:9], v[170:173], v[210:213], v[6:9]
	v_mfma_i32_16x16x64_i8 v[2:5], v[178:181], v[210:213], v[2:5]
	s_setprio 0
	s_barrier
	s_add_i32 s59, s59, 2
	s_addk_i32 s55, 0x100
	s_addk_i32 s58, 0x100
	s_cmp_gt_u32 s59, 5
	s_cbranch_scc0 .LBB0_1072
	s_and_b64 vcc, exec, s[20:21]
	s_cbranch_vccz .LBB0_1075
	s_barrier
